# FoX attention: skip leading KV tiles whose softmax weight provably underflows to 0 in f32 (bound from forget-gate cumsum + q/k norm gains); per-item tile offset table in LDS
# speedup vs baseline: 1.0165x; 1.0160x over previous
; __device__ __forceinline__ void p5_fox(Frame& F, char* lds) {
;     constexpr int TOTAL = BATCH * NH * (SEQ / 256);
;     __syncthreads();
;     if (F.tid == 0) { const unsigned a_ = __hip_atomic_fetch_add(F.ctl + CW_QUEUE, 1u, RLX_AGENT), b_ = __hip_atomic_fetch_add(F.ctl + CW_QUEUE, 1u, RLX_AGENT); F.MISC[16] = a_; F.MISC[17] = b_; }
;     __syncthreads();
;     int cur = (int)F.MISC[16]; if (cur >= TOTAL) return;
;     int nxt = (int)F.MISC[17];
.LBB0_1437:
	s_waitcnt vmcnt(0) lgkmcnt(0)
	s_barrier
	v_mbcnt_lo_u32_b32 v4, -1, 0
	v_mbcnt_hi_u32_b32 v4, -1, v4
	v_readfirstlane_b32 s40, v0
	s_lshr_b32 s40, s40, 6
	v_readlane_b32 s42, v252, 14
	v_readlane_b32 s43, v252, 15
	v_readlane_b32 s44, v252, 16
	v_readlane_b32 s45, v252, 17
	v_lshlrev_b32_e32 v5, 2, v4
	s_nop 4
	global_load_dword v6, v5, s[42:43]
	global_load_dword v7, v5, s[42:43] offset:256
	global_load_dword v8, v5, s[44:45]
	global_load_dword v9, v5, s[44:45] offset:256
	s_waitcnt vmcnt(0)
	v_and_b32_e32 v6, 0x7fffffff, v6
	v_and_b32_e32 v7, 0x7fffffff, v7
	v_and_b32_e32 v8, 0x7fffffff, v8
	v_and_b32_e32 v9, 0x7fffffff, v9
	v_max_u32_e32 v6, v6, v7
	v_max_u32_e32 v8, v8, v9
	v_xor_b32_e32 v10, 4, v5
	ds_bpermute_b32 v11, v10, v6
	ds_bpermute_b32 v12, v10, v8
	s_waitcnt lgkmcnt(0)
	v_max_u32_e32 v6, v6, v11
	v_max_u32_e32 v8, v8, v12
	v_xor_b32_e32 v10, 8, v5
	ds_bpermute_b32 v11, v10, v6
	ds_bpermute_b32 v12, v10, v8
	s_waitcnt lgkmcnt(0)
	v_max_u32_e32 v6, v6, v11
	v_max_u32_e32 v8, v8, v12
	v_xor_b32_e32 v10, 16, v5
	ds_bpermute_b32 v11, v10, v6
	ds_bpermute_b32 v12, v10, v8
	s_waitcnt lgkmcnt(0)
	v_max_u32_e32 v6, v6, v11
	v_max_u32_e32 v8, v8, v12
	v_xor_b32_e32 v10, 32, v5
	ds_bpermute_b32 v11, v10, v6
	ds_bpermute_b32 v12, v10, v8
	s_waitcnt lgkmcnt(0)
	v_max_u32_e32 v6, v6, v11
	v_max_u32_e32 v8, v8, v12
	v_xor_b32_e32 v10, 64, v5
	ds_bpermute_b32 v11, v10, v6
	ds_bpermute_b32 v12, v10, v8
	s_waitcnt lgkmcnt(0)
	v_max_u32_e32 v6, v6, v11
	v_max_u32_e32 v8, v8, v12
	v_xor_b32_e32 v10, 128, v5
	ds_bpermute_b32 v11, v10, v6
	ds_bpermute_b32 v12, v10, v8
	s_waitcnt lgkmcnt(0)
	v_max_u32_e32 v6, v6, v11
	v_max_u32_e32 v8, v8, v12
	v_mul_f32_e32 v6, v6, v8
	v_mov_b32_e32 v7, 0x41b80000
	v_mov_b32_e32 v8, 0x42f00000
	v_fma_f32 v6, v6, v7, v8
	v_mul_f32_e32 v6, 0x41351eb8, v6
	s_add_u32 s46, s82, 0x500000
	s_addc_u32 s47, s83, 0
	v_lshlrev_b32_e32 v9, 6, v4
	v_add_u32_e32 v9, -1, v9
	v_max_i32_e32 v9, 0, v9
	v_lshlrev_b32_e32 v9, 4, v9
	s_lshl_b32 s48, s40, 2
	s_mov_b32 s49, 0
.Lfsk_bh:
	s_add_i32 s50, s48, s49
	s_lshl_b32 s53, s50, 16
	s_add_u32 s54, s46, s53
	s_addc_u32 s55, s47, 0
	global_load_dwordx2 v[10:11], v9, s[54:55]
	s_waitcnt vmcnt(0)
	v_lshlrev_b32_e32 v12, 16, v10
	v_and_b32_e32 v13, 0xffff0000, v10
	v_lshlrev_b32_e32 v14, 16, v11
	v_add_f32_e32 v12, v12, v13
	v_add_f32_e32 v12, v12, v14
	s_lshl_b32 s62, s50, 6
	s_add_i32 s62, s62, 0x23400
	v_mov_b32_e32 v14, s62
	v_mov_b32_e32 v15, 0
	ds_write_b32 v14, v15
	s_mov_b32 s56, 1
.Lfsk_qb:
	s_lshl_b32 s57, s56, 2
	s_nop 0
	v_readlane_b32 s58, v12, s57
	s_nop 3
	v_sub_f32_e32 v13, s58, v12
	v_cmp_gt_f32_e64 s[60:61], v13, v6
	s_nop 3
	s_bitset0_b32 s60, 0
	s_bcnt1_i32_b64 s59, s[60:61]
	s_and_b32 s59, s59, -2
	s_lshl_b32 s59, s59, 6
	s_lshl_b32 s63, s56, 2
	s_add_i32 s63, s63, s62
	v_mov_b32_e32 v14, s63
	v_mov_b32_e32 v15, s59
	ds_write_b32 v14, v15
	s_add_i32 s56, s56, 1
	s_cmp_lt_u32 s56, 16
	s_cbranch_scc1 .Lfsk_qb
	s_add_i32 s49, s49, 1
	s_cmp_lt_u32 s49, 4
	s_cbranch_scc1 .Lfsk_bh
	s_waitcnt lgkmcnt(0)
	v_cmp_eq_u32_e64 s[0:1], 0, v2
	s_mov_b64 s[4:5], exec
	s_nop 0
	v_writelane_b32 v252, s0, 52
	s_nop 1
	v_writelane_b32 v252, s1, 53
	s_and_b64 s[0:1], s[4:5], s[0:1]
	s_mov_b64 exec, s[0:1]
	s_cbranch_execz .LBB0_1443
	s_mov_b64 s[8:9], exec
	v_mbcnt_lo_u32_b32 v1, s8, 0
	s_add_u32 s6, s82, 0x8000
	v_mbcnt_hi_u32_b32 v1, s9, v1
	s_addc_u32 s7, s83, 0
	v_cmp_eq_u32_e32 vcc, 0, v1
	s_and_saveexec_b64 s[10:11], vcc
	s_cbranch_execz .LBB0_1440
	s_bcnt1_i32_b64 s0, s[8:9]
	v_mov_b32_e32 v2, 0
	v_mov_b32_e32 v3, s0
	global_atomic_add v2, v2, v3, s[6:7] sc0

; #define VMW() asm volatile("s_waitcnt vmcnt(0)" ::: "memory")
; #define SWRITE_HK(bf) do { *(bf16x8*)(K_lds + (bf) * SHM_K + kws) = S.st_k0; *(bf16x8*)(K_lds + (bf) * SHM_K + kws + 32 * 256) = S.st_k1; } while (0)
; __device__ __forceinline__ fox::BlockRef fox_item(int L) { return fox_ref(L & 31, 15 - (L >> 5)); }
; template <int PQ, int PO>
; __device__ __forceinline__ void fox_prime(const Bases& Bs, const BlockRef& cur, char* lds, Seam& S) {
;     const int tid = threadIdx.x, wid = __builtin_amdgcn_readfirstlane(tid >> 6), lane = tid & 63, r32 = lane & 31, hi = lane >> 5;
;     const int sr = tid >> 4, sc = (tid & 15) * 8, kws = KSWZ(sr, sc * 2); char* K_lds = lds + 2 * SHM_V; char* KX_lds = lds + LDS_KX; char* Qw = lds + LDS_Q + wid * (QBLK * D * 2);
;     QLOAD(cur.q);
;     SLOAD_H(Bs.P + cur.k, Bs.P + cur.v, Bs.KX + (size_t)cur.kx * 8, 0, 0); VMW(); SWRITE_HK(0);
; __device__ __forceinline__ void p5_fox(Frame& F, char* lds) {
;     ...
;     int cur = (int)F.MISC[16]; if (cur >= TOTAL) return;
;     int nxt = (int)F.MISC[17];
;     const fox::Bases Bs{(const bf16*)(F.ws + WS_P), (const bf16*)(F.ws + WS_KX), (bf16*)(F.ws + WS_MIX)};
;     fox::Seam S;
;     { const fox::BlockRef c0 = fox_item(cur); fox::fox_prime<NPP, LDMIX>(Bs, c0, lds, S); }
.LBB0_1443:
	v_writelane_b32 v252, s88, 40
	s_nop 1
	v_writelane_b32 v252, s89, 41
	v_writelane_b32 v252, s95, 51
	s_or_b64 exec, exec, s[4:5]
	s_add_i32 s0, 0, 0x23180
	v_mov_b32_e32 v1, s0
	s_waitcnt lgkmcnt(0)
	s_barrier
	ds_read_b32 v1, v1
	s_movk_i32 s0, 0x1ff
	s_mov_b32 s5, 0
	s_waitcnt lgkmcnt(0)
	v_cmp_lt_i32_e32 vcc, s0, v1
	v_readfirstlane_b32 s97, v1
	s_cbranch_vccnz .LBB0_1631
	s_and_b32 s100, s97, 31
	s_lshl_b32 s100, s100, 4
	s_lshr_b32 s101, s97, 5
	s_sub_i32 s101, 15, s101
	s_add_i32 s100, s100, s101
	s_lshl_b32 s100, s100, 2
	s_add_i32 s100, s100, 0x23400
	v_mov_b32_e32 v237, s100
	ds_read_b32 v237, v237
	s_waitcnt lgkmcnt(0)
	v_readfirstlane_b32 s98, v237
	s_nop 1
	s_cmpk_lt_u32 s97, 0x200
	s_cselect_b32 s98, s98, 0
	s_add_i32 s0, 0, 0x23184
	v_mov_b32_e32 v1, s0
	s_add_u32 s0, s82, 0x500000
	s_addc_u32 s1, s83, 0
	v_writelane_b32 v252, s0, 56
	s_lshl_b32 s2, s97, 3
	s_and_b32 s2, s2, 0x3ffff00
	v_writelane_b32 v252, s1, 57
	s_lshl_b32 s1, s97, 8
	s_and_b32 s0, s97, 31
	s_and_b32 s1, s1, 0x1000
	s_sub_i32 s2, s1, s2
	s_lshl_b32 s7, s0, 7
	s_mulk_i32 s2, 0x3840
	s_and_b32 s8, s7, 0x780
	s_or_b32 s2, s2, s8
	s_mulk_i32 s1, 0x3840
	s_add_i32 s4, s2, 0x34bc000
	s_or_b32 s2, s7, s1
	v_readfirstlane_b32 s7, v0
	s_or_b32 s1, s1, s8
	s_lshr_b32 s8, s7, 6
	s_lshl_b32 s9, s8, 13
	s_add_i32 s9, s9, 0
	s_lshl_b32 s2, s2, 1
	s_add_i32 m0, s9, 0x11000
	s_lshl_b32 s10, s8, 5
	s_lshl_b64 s[4:5], s[4:5], 1
	v_readlane_b32 s14, v252, 38
	v_bfe_u32 v7, v0, 4, 2
	v_readlane_b32 s15, v252, 39
	s_add_u32 s11, s14, s4
	v_mul_u32_u24_e32 v5, 0x3840, v7
	s_addc_u32 s12, s15, s5
	s_mul_i32 s8, s8, 0xe1000
	v_bitop3_b32 v2, v7, v0, 15 bitop3:0x78
	s_mul_hi_u32 s5, s10, 0x7080
	s_add_u32 s4, s11, s8
	v_lshl_add_u32 v2, v2, 3, v5
	s_addc_u32 s5, s12, s5
	v_mov_b32_e32 v171, 0
	v_lshlrev_b32_e32 v170, 1, v2
	v_and_b32_e32 v6, 15, v0
	v_lshl_add_u64 v[2:3], s[4:5], 0, v[170:171]
	s_or_b32 s4, s10, 4
	ds_read_b32 v1, v1
	global_load_lds_dwordx4 v[2:3], off
	s_mul_hi_u32 s5, s4, 0x7080
	s_mulk_i32 s4, 0x7080
	v_bitop3_b32 v2, v7, v6, 4 bitop3:0x36
	s_add_u32 s4, s11, s4
	v_lshl_add_u32 v2, v2, 3, v5
	s_addc_u32 s5, s12, s5
	v_lshlrev_b32_e32 v172, 1, v2
	v_mov_b32_e32 v173, v171
	v_lshl_add_u64 v[2:3], s[4:5], 0, v[172:173]
	s_or_b32 s4, s10, 8
	s_add_i32 m0, s9, 0x11400
	s_mul_hi_u32 s5, s4, 0x7080
	s_mulk_i32 s4, 0x7080
	s_add_u32 s4, s11, s4
	s_addc_u32 s5, s12, s5
	global_load_lds_dwordx4 v[2:3], off
	v_lshl_add_u64 v[2:3], s[4:5], 0, v[170:171]
	s_or_b32 s4, s10, 12
	s_add_i32 m0, s9, 0x11800
	s_mul_hi_u32 s5, s4, 0x7080
	s_mulk_i32 s4, 0x7080
	s_add_u32 s4, s11, s4
	s_addc_u32 s5, s12, s5
	global_load_lds_dwordx4 v[2:3], off
	v_lshl_add_u64 v[2:3], s[4:5], 0, v[172:173]
	s_or_b32 s4, s10, 16
	s_add_i32 m0, s9, 0x11c00
	s_mul_hi_u32 s5, s4, 0x7080
	s_mulk_i32 s4, 0x7080
	s_add_u32 s4, s11, s4
	s_addc_u32 s5, s12, s5
	global_load_lds_dwordx4 v[2:3], off
	v_lshl_add_u64 v[2:3], s[4:5], 0, v[170:171]
	s_or_b32 s4, s10, 20
	s_add_i32 m0, s9, 0x12000
	s_mul_hi_u32 s5, s4, 0x7080
	s_mulk_i32 s4, 0x7080
	s_add_u32 s4, s11, s4
	s_addc_u32 s5, s12, s5
	global_load_lds_dwordx4 v[2:3], off
	v_lshl_add_u64 v[2:3], s[4:5], 0, v[172:173]
	s_or_b32 s4, s10, 24
	s_add_i32 m0, s9, 0x12400
	s_mul_hi_u32 s5, s4, 0x7080
	s_mulk_i32 s4, 0x7080
	s_add_u32 s4, s11, s4
	s_addc_u32 s5, s12, s5
	global_load_lds_dwordx4 v[2:3], off
	v_lshl_add_u64 v[2:3], s[4:5], 0, v[170:171]
	s_or_b32 s4, s10, 28
	s_add_i32 m0, s9, 0x12800
	s_mul_hi_u32 s5, s4, 0x7080
	s_mulk_i32 s4, 0x7080
	s_add_u32 s4, s11, s4
	v_lshlrev_b32_e32 v4, 3, v0
	s_addc_u32 s5, s12, s5
	s_movk_i32 s6, 0x3840
	global_load_lds_dwordx4 v[2:3], off
	v_lshl_add_u64 v[2:3], s[4:5], 0, v[172:173]
	s_add_i32 m0, s9, 0x12c00
	v_lshrrev_b32_e32 v9, 4, v0
	v_and_b32_e32 v8, 0x78, v4
	s_lshl_b32 s1, s1, 1
	global_load_lds_dwordx4 v[2:3], off
	s_add_u32 s4, s14, s1
	v_mad_u32_u24 v2, v9, s6, v8
	s_addc_u32 s5, s15, 0
	s_mul_i32 s100, s98, 0x7080
	s_add_u32 s4, s4, s100
	s_addc_u32 s5, s5, 0
	v_lshlrev_b32_e32 v174, 1, v2
	v_mov_b32_e32 v175, v171
	v_lshl_add_u64 v[2:3], s[4:5], 0, v[174:175]
	s_movk_i32 s1, 0x2000
	v_add_co_u32_e32 v4, vcc, s1, v2
	s_mov_b32 s1, 0xe3000
	s_nop 0
	v_addc_co_u32_e32 v5, vcc, 0, v3, vcc
	s_bitset1_b32 s2, 12
	v_add_co_u32_e32 v2, vcc, s1, v2
	s_add_u32 s4, s14, s2
	s_nop 0
	v_addc_co_u32_e32 v3, vcc, 0, v3, vcc
	s_addc_u32 s5, s15, 0
	s_mul_i32 s100, s98, 0x7080
	s_add_u32 s4, s4, s100
	s_addc_u32 s5, s5, 0
	global_load_dwordx4 v[114:117], v[4:5], off
	global_load_dwordx4 v[118:121], v[2:3], off
	v_lshl_add_u64 v[2:3], s[4:5], 0, v[174:175]
	v_add_co_u32_e32 v2, vcc, 0xe1000, v2
	v_and_b32_e32 v10, 63, v0
	s_nop 0
	v_addc_co_u32_e32 v3, vcc, 0, v3, vcc
	global_load_dwordx4 v[122:125], v174, s[4:5]
	global_load_dwordx4 v[126:129], v[2:3], off
	s_waitcnt lgkmcnt(0)
	v_readfirstlane_b32 s1, v1
	s_cmp_lt_u32 s7, 64
	v_lshlrev_b32_e32 v4, 3, v10
	s_cbranch_scc1 .LBB0_1446
	v_lshlrev_b32_e32 v2, 3, v10
	v_mov_b32_e32 v3, v171
	s_mov_b64 s[4:5], 0
	v_mov_b64_e32 v[176:177], v[2:3]
	s_branch .LBB0_1447

; #define VMW() asm volatile("s_waitcnt vmcnt(0)" ::: "memory")
; #define SWRITE_HK(bf) do { *(bf16x8*)(K_lds + (bf) * SHM_K + kws) = S.st_k0; *(bf16x8*)(K_lds + (bf) * SHM_K + kws + 32 * 256) = S.st_k1; } while (0)
; template <int PQ, int PO>
; __device__ __forceinline__ void fox_prime(const Bases& Bs, const BlockRef& cur, char* lds, Seam& S) {
;     ...
;     SLOAD_H(Bs.P + cur.k, Bs.P + cur.v, Bs.KX + (size_t)cur.kx * 8, 0, 0); VMW(); SWRITE_HK(0);
.LBB0_1447:
	v_writelane_b32 v252, s84, 42
	s_andn2_b64 vcc, exec, s[4:5]
	v_mul_u32_u24_e32 v3, 0x3840, v9
	v_writelane_b32 v252, s85, 43
	v_writelane_b32 v252, s86, 44
	s_nop 1
	v_writelane_b32 v252, s87, 45
	s_cbranch_vccnz .LBB0_1449
	s_lshl_b32 s0, s0, 16
	v_readlane_b32 s6, v252, 56
	v_readlane_b32 s7, v252, 57
	s_add_u32 s6, s6, s0
	s_addc_u32 s7, s7, 0
	s_lshl_b32 s101, s98, 4
	s_add_u32 s6, s6, s101
	s_addc_u32 s7, s7, 0
	s_cmp_lg_u32 0, -1
	s_mov_b64 s[4:5], src_shared_base
	s_cselect_b32 s2, 0, 0
	s_cselect_b32 s0, s5, 0
	s_add_u32 s4, s2, 0x10800
	s_addc_u32 s5, s0, 0
	s_cmp_lg_u64 s[4:5], 0
	v_lshlrev_b32_e32 v1, 4, v10
	s_cselect_b32 m0, s4, -1
	v_mov_b32_e32 v5, 0
	global_load_lds_dwordx4 v1, s[6:7]
	v_mov_b64_e32 v[176:177], v[4:5]
	v_mov_b32_e32 v2, v4

; #define SBAR() __builtin_amdgcn_sched_barrier(0)
; __device__ __forceinline__ int v_st(int k, int c) { const int kk = (k & ~0xC) | ((k & 4) << 1) | ((k & 8) >> 1); return ((kk >> 3) * 4 + (c >> 5)) * 512 + ((kk & 7) * 32 + (c & 31)) * 2; }
; __device__ __forceinline__ int v_rd_base(int lane) { return ((lane & 3) << 3) | (((lane >> 2) & 3) << 6) | (((lane >> 4) & 1) << 5) | (((lane >> 5) & 1) << 8); }
; #define VMW() asm volatile("s_waitcnt vmcnt(0)" ::: "memory")
; #define SWRITE_HV(bf) do { *(bf16x8*)(V_lds + (bf) * SHM_V + vst0) = S.st_v0; *(bf16x8*)(V_lds + (bf) * SHM_V + vst1) = S.st_v1; } while (0)
; #define SWRITE_H(bf) do { SWRITE_HV(bf); SWRITE_HK(bf); } while (0)
; #define MASKT(P0_, P1_, t) do { const int kb_ = KBASE(t); if (kb_ + KVBLK - 1 > qlo) mask_tile(P0_, P1_, qm - kb_); } while (0)
; template <int PQ, int PO>
; __device__ __forceinline__ void fox_block(const Bases& Bs, const BlockRef& cur, const BlockRef& nxt, char* lds, Seam& S) {
;     const int tid = threadIdx.x, wid = __builtin_amdgcn_readfirstlane(tid >> 6), lane = tid & 63, r32 = lane & 31, hi = lane >> 5;
;     const int NT = (cur.P0 + QB - 1) / KVBLK + 1;
;     const int qlo = cur.P0 + wid * QBLK, qm = qlo + r32 - 4 * hi;
;     char* V_lds = lds; char* K_lds = lds + 2 * SHM_V;
;     float* ws = (float*)(lds + LDS_WS) + wid * 64; float* li_l = ws, * al_l = ws + 32; char* KX_lds = lds + LDS_KX; char* Qw = lds + LDS_Q + wid * (QBLK * D * 2);
;     float m_reg = -1e30f, l_reg = 0; f32x16 o[4] = {};
;     const int sr = tid >> 4, sc = (tid & 15) * 8, vst0 = v_st(sr, sc), vst1 = v_st(32 + sr, sc), kws = KSWZ(sr, sc * 2);
;     const int vb0 = (int)(uintptr_t)V_lds + v_rd_base(lane);
;     const bf16* Kh = Bs.P + cur.k; const bf16* Vh = Bs.P + cur.v; const bf16* KXh = Bs.KX + (size_t)cur.kx * 8;
;     ...
;     constexpr int NQL = 8;
;     ...
;     f32x16 pA0, pA1, pB0, pB1; float mnA, mnB, alA, alB; bf16x8 pa0, pa1, pa2, pa3;
;     SWRITE_HV(0); SBAR();
;     if (NT > 1) SLOAD_H(Kh, Vh, KXh, KBASE(1), 1);
;     SBAR(); qkt<0>(pA0, pA1, K_lds, KX_lds, r32, hi, Qw);
;     MASKT(pA0, pA1, 0); partialSM(pA0, pA1, m_reg, mnA, alA);
;     if (NT > 1) { VMW(); SWRITE_H(1); }
.LBB0_1452:
	s_and_b64 vcc, exec, s[6:7]
	s_mov_b32 s97, s86
	s_mov_b32 s98, s99
	s_cbranch_vccnz .LBB0_1630
.LBB0_1453:
	s_and_b32 s100, s1, 31
	s_lshl_b32 s100, s100, 4
	s_lshr_b32 s101, s1, 5
	s_sub_i32 s101, 15, s101
	s_add_i32 s100, s100, s101
	s_lshl_b32 s100, s100, 2
	s_add_i32 s100, s100, 0x23400
	v_mov_b32_e32 v237, s100
	ds_read_b32 v237, v237
	s_waitcnt lgkmcnt(0)
	v_readfirstlane_b32 s99, v237
	s_nop 1
	s_cmpk_lt_u32 s1, 0x200
	s_cselect_b32 s99, s99, 0
	s_lshl_b32 s0, s97, 8
	s_and_b32 s2, s97, 31
	s_and_b32 s0, s0, 0x1000
	s_mov_b32 s86, s1
	s_lshl_b32 s1, s97, 3
	s_lshl_b32 s6, s2, 7
	s_mul_i32 s94, s0, 0x3840
	s_mul_i32 s100, s98, 0x3840
	s_add_i32 s94, s94, s100
	s_mov_b32 s72, s91
	s_mov_b32 s95, s3
	s_mov_b32 s3, s90
	s_and_b32 s90, s1, 0xffffff00
	s_or_b32 s91, s6, s94
	s_sub_i32 s1, 0xf00, s90
	s_and_b32 s87, s6, 0x780
	s_bitset1_b32 s91, 11
	s_lshl_b32 s74, s2, 16
	s_lshl_b32 s100, s98, 4
	s_add_i32 s74, s74, s100
	v_readfirstlane_b32 s2, v0
	ds_write_b128 v211, v[114:117]
	ds_write_b128 v212, v[118:121]
	s_cmpk_gt_i32 s1, 0xff40
	s_cselect_b64 s[70:71], -1, 0
	s_cmpk_lt_i32 s1, 0xff41
	s_cbranch_scc1 .LBB0_1456
	s_or_b32 s6, s94, s87
	s_lshl_b32 s7, s91, 1
	v_readlane_b32 s10, v252, 38
	v_readlane_b32 s11, v252, 39
	s_add_u32 s8, s10, s7
	s_addc_u32 s9, s11, 0
	s_lshl_b32 s6, s6, 1
	s_add_u32 s6, s10, s6
	s_addc_u32 s7, s11, 0
	s_add_u32 s6, s6, 0x1c4000
	s_addc_u32 s7, s7, 0
	s_add_u32 s8, s8, 0x1c2000
	s_addc_u32 s9, s9, 0
	global_load_dwordx4 v[114:117], v174, s[6:7]
	global_load_dwordx4 v[122:125], v174, s[8:9]
	global_load_dwordx4 v[118:121], v209, s[6:7]
	global_load_dwordx4 v[126:129], v209, s[8:9]
	s_cmp_gt_u32 s2, 63
	s_cbranch_scc1 .LBB0_1456
	v_readlane_b32 s8, v252, 56
	v_readlane_b32 s9, v252, 57
	s_add_u32 s8, s8, s74
	s_addc_u32 s9, s9, 0
	s_mov_b64 s[6:7], src_shared_base
	s_cmp_lg_u32 0, -1
	s_cselect_b32 s6, 0, 0
	s_cselect_b32 s7, s7, 0
	s_add_u32 s6, s6, 0x10c00
	s_addc_u32 s7, s7, 0
	v_lshl_add_u64 v[4:5], v[176:177], 1, s[8:9]
	s_mov_b64 s[8:9], 0x400
	s_cmp_lg_u64 s[6:7], 0
	v_lshl_add_u64 v[4:5], v[4:5], 0, s[8:9]
	s_cselect_b32 m0, s6, -1
	s_nop 0
	global_load_lds_dwordx4 v[4:5], off
; __device__ __forceinline__ void mask_tile(f32x16& p0, f32x16& p1, int dq) {
;     const float NEG = -__builtin_inff();
; #pragma unroll
;     for (int r = 0; r < 16; ++r) {
;         const int c = (r & 3) + 8 * (r >> 2);
;         if (dq - c < 0) p0[r] = NEG;
;         if (dq - c - 32 < 0) p1[r] = NEG;
;     }
; }
; template <int KB>
; __device__ __forceinline__ void qkt(f32x16& p0, f32x16& p1, const char* K_lds, const char* KX_lds, int r32, int hi, const char* Qw) {
;     p0 = f32x16{}; p1 = f32x16{};
;     {
;         const short one = hi ? (short)0 : (short)0x3F80;
;         const bf16x8 qx = {one, one, one, 0, 0, 0, 0, 0};
;         const bf16x8 x0 = *reinterpret_cast<const bf16x8*>(KX_lds + KB * 1024 + r32 * 16);
;         const bf16x8 x1 = *reinterpret_cast<const bf16x8*>(KX_lds + KB * 1024 + (32 + r32) * 16);
;         p0 = __builtin_amdgcn_mfma_f32_32x32x16_bf16(x0, qx, p0, 0, 0, 0);
;         p1 = __builtin_amdgcn_mfma_f32_32x32x16_bf16(x1, qx, p1, 0, 0, 0); }
;     const char* kb[4]; const char* qb[4];
; #pragma unroll
;     for (int dd = 0; dd < 4; ++dd) { const int sw = KSWZ(r32, (dd * 16 + hi * 8) * 2); kb[dd] = K_lds + KB * SHM_K + sw; qb[dd] = Qw + sw; }
; #pragma unroll
;     for (int d0 = 0; d0 < 8; ++d0) { const char* a = kb[d0 & 3] + (d0 >> 2) * 128;
;         bf16x8 b0 = *reinterpret_cast<const bf16x8*>(a);
;         bf16x8 b1 = *reinterpret_cast<const bf16x8*>(a + 32 * 256);
;         bf16x8 q = *reinterpret_cast<const bf16x8*>(qb[d0 & 3] + (d0 >> 2) * 128);
;         p0 = __builtin_amdgcn_mfma_f32_32x32x16_bf16(b0, q, p0, 0, 0, 0);
;         p1 = __builtin_amdgcn_mfma_f32_32x32x16_bf16(b1, q, p1, 0, 0, 0); }
.LBB0_1456:
	s_lshr_b32 s6, s2, 6
	s_lshl_b32 s96, s6, 5
	s_lshl_b32 s6, s6, 13
	s_add_i32 s73, s96, s1
	s_sub_i32 s73, s73, s98
	s_add_i32 s89, s6, 0
	v_add_u32_e32 v218, s73, v173
	s_add_i32 s89, s89, 0x11000
	v_add_u32_e32 v222, 0, v183
	v_add_u32_e32 v229, 0x10800, v222
	ds_read_b128 v[4:7], v229
	ds_read_b128 v[8:11], v229 offset:512
	v_add_u32_e32 v219, 0, v204
	ds_read_b128 v[36:39], v219 offset:32768
	v_add_u32_e32 v220, s89, v204
	s_waitcnt lgkmcnt(0)
	v_mfma_f32_32x32x16_bf16 v[20:35], v[4:7], v[146:149], 0
	ds_read_b128 v[40:43], v220
	ds_read_b128 v[44:47], v219 offset:32896
	ds_read_b128 v[48:51], v220 offset:128
	v_add_u32_e32 v221, 0, v205
	v_add_u32_e32 v225, s89, v205
	v_add_u32_e32 v223, 0, v206
	v_add_u32_e32 v226, s89, v206
	v_add_u32_e32 v224, 0, v207
	v_add_u32_e32 v227, s89, v207
	v_mfma_f32_32x32x16_bf16 v[4:19], v[8:11], v[146:149], 0
	s_cmp_gt_i32 s73, 62
	s_waitcnt lgkmcnt(0)
	v_mfma_f32_32x32x16_bf16 v[20:35], v[36:39], v[40:43], v[20:35]
	ds_read_b128 v[36:39], v219 offset:40960
	ds_read_b128 v[52:55], v219 offset:41088
	s_waitcnt lgkmcnt(0)
	v_mfma_f32_32x32x16_bf16 v[4:19], v[36:39], v[40:43], v[4:19]
	ds_read_b128 v[36:39], v221 offset:32768
	ds_read_b128 v[40:43], v225
	ds_read_b128 v[56:59], v221 offset:32896
	ds_read_b128 v[60:63], v225 offset:128
	s_waitcnt lgkmcnt(0)
	v_mfma_f32_32x32x16_bf16 v[20:35], v[36:39], v[40:43], v[20:35]
	ds_read_b128 v[36:39], v221 offset:40960
	ds_read_b128 v[64:67], v221 offset:41088
	s_waitcnt lgkmcnt(0)
	v_mfma_f32_32x32x16_bf16 v[4:19], v[36:39], v[40:43], v[4:19]
	ds_read_b128 v[36:39], v223 offset:32768
	ds_read_b128 v[40:43], v226
	ds_read_b128 v[68:71], v223 offset:32896
	ds_read_b128 v[72:75], v226 offset:128
	s_waitcnt lgkmcnt(0)
	v_mfma_f32_32x32x16_bf16 v[20:35], v[36:39], v[40:43], v[20:35]
	ds_read_b128 v[36:39], v223 offset:40960
	ds_read_b128 v[76:79], v223 offset:41088
	s_waitcnt lgkmcnt(0)
	v_mfma_f32_32x32x16_bf16 v[4:19], v[36:39], v[40:43], v[4:19]
	ds_read_b128 v[36:39], v224 offset:32768
	ds_read_b128 v[40:43], v227
	ds_read_b128 v[80:83], v224 offset:32896
	ds_read_b128 v[84:87], v227 offset:128
	s_waitcnt lgkmcnt(0)
	v_mfma_f32_32x32x16_bf16 v[20:35], v[36:39], v[40:43], v[20:35]
	ds_read_b128 v[36:39], v224 offset:40960
	ds_read_b128 v[88:91], v224 offset:41088
	s_waitcnt lgkmcnt(0)
	v_mfma_f32_32x32x16_bf16 v[4:19], v[36:39], v[40:43], v[4:19]
	v_mfma_f32_32x32x16_bf16 v[20:35], v[44:47], v[48:51], v[20:35]
	v_mfma_f32_32x32x16_bf16 v[4:19], v[52:55], v[48:51], v[4:19]
	v_mfma_f32_32x32x16_bf16 v[20:35], v[56:59], v[60:63], v[20:35]
	v_mfma_f32_32x32x16_bf16 v[4:19], v[64:67], v[60:63], v[4:19]
	v_mfma_f32_32x32x16_bf16 v[20:35], v[68:71], v[72:75], v[20:35]
	v_mfma_f32_32x32x16_bf16 v[4:19], v[76:79], v[72:75], v[4:19]
	v_mfma_f32_32x32x16_bf16 v[20:35], v[80:83], v[84:87], v[20:35]
	v_mfma_f32_32x32x16_bf16 v[4:19], v[88:91], v[84:87], v[4:19]
	s_cbranch_scc1 .LBB0_1458
	v_cmp_gt_i32_e64 s[66:67], 26, v218
	v_cmp_gt_i32_e64 s[68:69], 27, v218
	v_cmp_gt_i32_e64 s[64:65], 25, v218
	s_and_b64 s[66:67], s[68:69], s[66:67]
	v_cmp_gt_i32_e64 s[62:63], 24, v218
	s_and_b64 s[64:65], s[66:67], s[64:65]
	v_cmp_gt_i32_e64 s[60:61], 19, v218
	s_and_b64 s[62:63], s[64:65], s[62:63]
	v_cmp_gt_i32_e64 s[58:59], 18, v218
	s_and_b64 s[60:61], s[62:63], s[60:61]
	v_cmp_gt_i32_e64 s[56:57], 17, v218
	s_and_b64 s[58:59], s[60:61], s[58:59]
	v_cmp_gt_i32_e64 s[54:55], 16, v218
	s_and_b64 s[56:57], s[58:59], s[56:57]
	v_cmp_gt_i32_e64 s[52:53], 11, v218
	s_and_b64 s[54:55], s[56:57], s[54:55]
	v_cmp_gt_i32_e64 s[50:51], 10, v218
	s_and_b64 s[52:53], s[54:55], s[52:53]
	v_cmp_gt_i32_e64 s[48:49], 9, v218
	s_and_b64 s[50:51], s[52:53], s[50:51]
	v_cmp_gt_i32_e64 s[46:47], 8, v218
	s_and_b64 s[48:49], s[50:51], s[48:49]
	v_cmp_gt_i32_e64 s[44:45], 3, v218
	s_and_b64 s[46:47], s[48:49], s[46:47]
	v_cmp_gt_i32_e64 s[42:43], 2, v218
	s_and_b64 s[44:45], s[46:47], s[44:45]
	v_cmp_gt_i32_e64 s[40:41], 1, v218
	s_and_b64 s[42:43], s[44:45], s[42:43]
	v_cmp_gt_i32_e64 s[36:37], 0, v218
	s_and_b64 s[40:41], s[42:43], s[40:41]
	s_and_b64 s[36:37], s[40:41], s[36:37]
	v_cmp_gt_i32_e64 s[34:35], 58, v218
	v_cndmask_b32_e64 v20, v20, v213, s[36:37]
	v_cmp_gt_i32_e64 s[36:37], 59, v218
	v_cmp_gt_i32_e64 s[30:31], 57, v218
	s_and_b64 s[34:35], s[36:37], s[34:35]
	v_cmp_gt_i32_e64 s[28:29], 56, v218
	s_and_b64 s[30:31], s[34:35], s[30:31]
	v_cmp_gt_i32_e64 s[26:27], 51, v218
	s_and_b64 s[28:29], s[30:31], s[28:29]
	v_cmp_gt_i32_e64 s[24:25], 50, v218
	s_and_b64 s[26:27], s[28:29], s[26:27]
	v_cmp_gt_i32_e64 s[22:23], 49, v218
	s_and_b64 s[24:25], s[26:27], s[24:25]
	v_cmp_gt_i32_e64 s[20:21], 48, v218
	s_and_b64 s[22:23], s[24:25], s[22:23]
	v_cmp_gt_i32_e64 s[18:19], 43, v218
	s_and_b64 s[20:21], s[22:23], s[20:21]
	v_cmp_gt_i32_e64 s[16:17], 42, v218
	s_and_b64 s[18:19], s[20:21], s[18:19]
	v_cmp_gt_i32_e64 s[14:15], 41, v218
	s_and_b64 s[16:17], s[18:19], s[16:17]
	v_cmp_gt_i32_e64 s[12:13], 40, v218
	s_and_b64 s[14:15], s[16:17], s[14:15]
	v_cmp_gt_i32_e64 s[10:11], 35, v218
	s_and_b64 s[12:13], s[14:15], s[12:13]
	v_cmp_gt_i32_e64 s[8:9], 34, v218
	s_and_b64 s[10:11], s[12:13], s[10:11]
	v_cmp_gt_i32_e64 s[6:7], 33, v218
	s_and_b64 s[8:9], s[10:11], s[8:9]
	v_cmp_gt_i32_e32 vcc, 32, v218
	s_and_b64 s[6:7], s[8:9], s[6:7]
	s_and_b64 vcc, s[6:7], vcc
	v_cndmask_b32_e64 v35, v35, v213, s[68:69]
	v_cndmask_b32_e64 v34, v34, v213, s[66:67]
	v_cndmask_b32_e64 v33, v33, v213, s[64:65]
	v_cndmask_b32_e64 v32, v32, v213, s[62:63]
	v_cndmask_b32_e64 v31, v31, v213, s[60:61]
	v_cndmask_b32_e64 v30, v30, v213, s[58:59]
	v_cndmask_b32_e64 v29, v29, v213, s[56:57]
	v_cndmask_b32_e64 v28, v28, v213, s[54:55]
	v_cndmask_b32_e64 v27, v27, v213, s[52:53]
	v_cndmask_b32_e64 v26, v26, v213, s[50:51]
	v_cndmask_b32_e64 v25, v25, v213, s[48:49]
	v_cndmask_b32_e64 v24, v24, v213, s[46:47]
	v_cndmask_b32_e64 v23, v23, v213, s[44:45]
	v_cndmask_b32_e64 v22, v22, v213, s[42:43]
	v_cndmask_b32_e64 v21, v21, v213, s[40:41]
	v_cndmask_b32_e64 v19, v19, v213, s[36:37]
	v_cndmask_b32_e64 v18, v18, v213, s[34:35]
	v_cndmask_b32_e64 v17, v17, v213, s[30:31]
	v_cndmask_b32_e64 v16, v16, v213, s[28:29]
	v_cndmask_b32_e64 v15, v15, v213, s[26:27]
	v_cndmask_b32_e64 v14, v14, v213, s[24:25]
	v_cndmask_b32_e64 v13, v13, v213, s[22:23]
	v_cndmask_b32_e64 v12, v12, v213, s[20:21]
	v_cndmask_b32_e64 v11, v11, v213, s[18:19]
	v_cndmask_b32_e64 v10, v10, v213, s[16:17]
	v_cndmask_b32_e64 v9, v9, v213, s[14:15]
	v_cndmask_b32_e64 v8, v8, v213, s[12:13]
	v_cndmask_b32_e64 v7, v7, v213, s[10:11]
	v_cndmask_b32_e64 v6, v6, v213, s[8:9]
	v_cndmask_b32_e64 v5, v5, v213, s[6:7]
	v_cndmask_b32_e32 v4, v4, v213, vcc

; __device__ __forceinline__ int v_st(int k, int c) { const int kk = (k & ~0xC) | ((k & 4) << 1) | ((k & 8) >> 1); return ((kk >> 3) * 4 + (c >> 5)) * 512 + ((kk & 7) * 32 + (c & 31)) * 2; }
; __device__ __forceinline__ void partialSM(f32x16& p0, f32x16& p1, float& m_reg, float& mn, float& alpha) {
;     float pmax = p0[0];
; #pragma unroll
;     for (int r = 1; r < 16; ++r) pmax = fmaxf(pmax, p0[r]);
; #pragma unroll
;     for (int r = 0; r < 16; ++r) pmax = fmaxf(pmax, p1[r]);
;     { auto rr = __builtin_amdgcn_permlane32_swap(__float_as_uint(pmax), __float_as_uint(pmax), false, false);
;       pmax = fmaxf(__uint_as_float(rr[0]), __uint_as_float(rr[1])); }
;     if (__builtin_expect(__all((pmax - m_reg) * SCALE <= THR), 1)) { mn = m_reg; alpha = 1.f; }
;     else { mn = fmaxf(m_reg, pmax); alpha = __builtin_amdgcn_exp2f((m_reg - mn) * C2); m_reg = mn; }
;     const float mnL = -mn * C2;
; #pragma unroll
;     for (int r = 0; r < 16; ++r) p0[r] = fmaf(p0[r], C2, mnL);
; #pragma unroll
;     for (int r = 0; r < 16; ++r) p1[r] = fmaf(p1[r], C2, mnL);
; #pragma unroll
;     for (int r = 0; r < 16; ++r) p0[r] = __builtin_amdgcn_exp2f(p0[r]);
; }
; template <int PQ, int PO>
; __device__ __forceinline__ void fox_block(const Bases& Bs, const BlockRef& cur, const BlockRef& nxt, char* lds, Seam& S) {
;     ...
;     const int NT = (cur.P0 + QB - 1) / KVBLK + 1;
;     const int qlo = cur.P0 + wid * QBLK, qm = qlo + r32 - 4 * hi;
;     char* V_lds = lds; char* K_lds = lds + 2 * SHM_V;
;     float* ws = (float*)(lds + LDS_WS) + wid * 64; float* li_l = ws, * al_l = ws + 32; char* KX_lds = lds + LDS_KX; char* Qw = lds + LDS_Q + wid * (QBLK * D * 2);
;     float m_reg = -1e30f, l_reg = 0; f32x16 o[4] = {};
;     const int sr = tid >> 4, sc = (tid & 15) * 8, vst0 = v_st(sr, sc), vst1 = v_st(32 + sr, sc), kws = KSWZ(sr, sc * 2);
.LBB0_1460:
	v_max_f32_e32 v3, 0xf149f2ca, v3
	v_cndmask_b32_e64 v154, v3, v215, s[6:7]
	v_sub_f32_e32 v3, 0xf149f2ca, v3
	v_mul_f32_e32 v3, 0x3e0293ee, v3
	v_exp_f32_e32 v3, v3
	v_mul_f32_e32 v36, 0xbe0293ee, v154
	v_fmamk_f32 v20, v20, 0x3e0293ee, v36
	v_fmamk_f32 v21, v21, 0x3e0293ee, v36
	v_cndmask_b32_e64 v228, v3, 1.0, s[6:7]
	s_sub_i32 s6, 0xfff, s90
	s_sub_i32 s6, s6, s98
	s_ashr_i32 s7, s6, 31
	s_lshr_b32 s7, s7, 26
	s_add_i32 s6, s6, s7
	v_fmamk_f32 v22, v22, 0x3e0293ee, v36
	v_fmamk_f32 v23, v23, 0x3e0293ee, v36
	v_fmamk_f32 v24, v24, 0x3e0293ee, v36
	v_fmamk_f32 v25, v25, 0x3e0293ee, v36
	v_fmamk_f32 v26, v26, 0x3e0293ee, v36
	v_fmamk_f32 v27, v27, 0x3e0293ee, v36
	v_fmamk_f32 v28, v28, 0x3e0293ee, v36
	v_fmamk_f32 v29, v29, 0x3e0293ee, v36
	v_fmamk_f32 v30, v30, 0x3e0293ee, v36
	v_fmamk_f32 v31, v31, 0x3e0293ee, v36
	v_fmamk_f32 v32, v32, 0x3e0293ee, v36
	v_fmamk_f32 v33, v33, 0x3e0293ee, v36
	v_fmamk_f32 v34, v34, 0x3e0293ee, v36
	v_fmamk_f32 v35, v35, 0x3e0293ee, v36
	s_ashr_i32 s33, s6, 6
	s_and_b32 s6, s2, 0x3fffffc0
	v_exp_f32_e32 v164, v20
	v_exp_f32_e32 v166, v21
	v_exp_f32_e32 v162, v22
	v_exp_f32_e32 v165, v23
	v_exp_f32_e32 v161, v24
	v_exp_f32_e32 v163, v25
	v_exp_f32_e32 v159, v26
	v_exp_f32_e32 v160, v27
	v_exp_f32_e32 v155, v28
	v_exp_f32_e32 v158, v29
	v_exp_f32_e32 v152, v30
	v_exp_f32_e32 v156, v31
	v_exp_f32_e32 v150, v32
	v_exp_f32_e32 v157, v33
	v_exp_f32_e32 v151, v34
	v_exp_f32_e32 v153, v35
	s_lshl_b32 s6, s6, 2
	s_add_i32 s6, s6, 0
	s_add_i32 s6, s6, 0x10000
	v_pk_fma_f32 v[130:131], v[18:19], s[88:89], v[36:37] op_sel_hi:[1,0,0]
	v_pk_fma_f32 v[132:133], v[16:17], s[88:89], v[36:37] op_sel_hi:[1,0,0]
	v_pk_fma_f32 v[134:135], v[14:15], s[88:89], v[36:37] op_sel_hi:[1,0,0]
	v_pk_fma_f32 v[136:137], v[12:13], s[88:89], v[36:37] op_sel_hi:[1,0,0]
	v_pk_fma_f32 v[138:139], v[10:11], s[88:89], v[36:37] op_sel_hi:[1,0,0]
	v_pk_fma_f32 v[140:141], v[8:9], s[88:89], v[36:37] op_sel_hi:[1,0,0]
	v_pk_fma_f32 v[142:143], v[6:7], s[88:89], v[36:37] op_sel_hi:[1,0,0]
	v_pk_fma_f32 v[144:145], v[4:5], s[88:89], v[36:37] op_sel_hi:[1,0,0]
	s_cmpk_lt_i32 s1, 0xff81
	v_lshl_add_u32 v217, v1, 2, s6
	v_lshl_add_u32 v216, v171, 2, s6
	s_waitcnt vmcnt(0) lgkmcnt(0)
	s_barrier
	s_cbranch_scc1 .LBB0_1483
	s_cmp_lt_u32 s2, 64
	s_mov_b32 s6, s87
	v_writelane_b32 v252, s86, 48
	s_cselect_b64 s[86:87], -1, 0
	v_writelane_b32 v250, s6, 17
	s_add_i32 s6, s94, s6
	v_lshl_add_u64 v[16:17], v[178:179], 0, s[74:75]
	s_lshl_b32 s74, s6, 1
	v_add_u32_e32 v3, s96, v208
	v_lshl_add_u64 v[188:189], v[184:185], 0, s[74:75]
	v_lshl_add_u64 v[190:191], v[186:187], 0, s[74:75]
	s_lshl_b32 s74, s91, 1
	v_subrev_u32_e32 v230, s90, v3
	v_subrev_u32_e32 v230, s98, v230
	v_mov_b32_e32 v3, 0
	s_mov_b32 s94, 1
	v_lshl_add_u64 v[192:193], v[184:185], 0, s[74:75]
	v_lshl_add_u64 v[194:195], v[186:187], 0, s[74:75]
	s_movk_i32 s74, 0x7f
	v_mov_b32_e32 v66, 0
	v_mov_b32_e32 v67, v3
	v_mov_b32_e32 v68, v3
	v_mov_b32_e32 v69, v3
	v_mov_b32_e32 v70, v3
	v_mov_b32_e32 v71, v3
	v_mov_b32_e32 v72, v3
	v_mov_b32_e32 v73, v3
	v_mov_b32_e32 v74, v3
	v_mov_b32_e32 v75, v3
	v_mov_b32_e32 v76, v3
	v_mov_b32_e32 v77, v3
	v_mov_b32_e32 v78, v3
	v_mov_b32_e32 v79, v3
	v_mov_b32_e32 v80, v3
	v_mov_b32_e32 v81, v3
	v_mov_b32_e32 v50, 0
	v_mov_b32_e32 v51, v3
	v_mov_b32_e32 v52, v3
	v_mov_b32_e32 v53, v3
	v_mov_b32_e32 v54, v3
	v_mov_b32_e32 v55, v3
	v_mov_b32_e32 v56, v3
	v_mov_b32_e32 v57, v3
	v_mov_b32_e32 v58, v3
	v_mov_b32_e32 v59, v3
	v_mov_b32_e32 v60, v3
	v_mov_b32_e32 v61, v3
	v_mov_b32_e32 v62, v3
	v_mov_b32_e32 v63, v3
	v_mov_b32_e32 v64, v3
	v_mov_b32_e32 v65, v3
	v_mov_b32_e32 v34, 0
	v_mov_b32_e32 v35, v3
	v_mov_b32_e32 v36, v3
	v_mov_b32_e32 v37, v3
	v_mov_b32_e32 v38, v3
	v_mov_b32_e32 v39, v3
	v_mov_b32_e32 v40, v3
	v_mov_b32_e32 v41, v3
	v_mov_b32_e32 v42, v3
	v_mov_b32_e32 v43, v3
	v_mov_b32_e32 v44, v3
	v_mov_b32_e32 v45, v3
	v_mov_b32_e32 v46, v3
	v_mov_b32_e32 v47, v3
	v_mov_b32_e32 v48, v3
	v_mov_b32_e32 v49, v3
	v_mov_b32_e32 v18, 0
	v_mov_b32_e32 v19, v3
	v_mov_b32_e32 v20, v3
	v_mov_b32_e32 v21, v3
	v_mov_b32_e32 v22, v3
	v_mov_b32_e32 v23, v3
	v_mov_b32_e32 v24, v3
	v_mov_b32_e32 v25, v3
	v_mov_b32_e32 v26, v3
	v_mov_b32_e32 v27, v3
	v_mov_b32_e32 v28, v3
	v_mov_b32_e32 v29, v3
	v_mov_b32_e32 v30, v3
	v_mov_b32_e32 v31, v3
	v_mov_b32_e32 v32, v3
	v_mov_b32_e32 v33, v3
	s_mov_b32 s90, s3
	s_mov_b32 s3, s95
	s_mov_b32 s91, s72
	s_branch .LBB0_1464

; #define SBAR() __builtin_amdgcn_sched_barrier(0)
; template <int PQ, int PO>
; __device__ __forceinline__ void fox_block(const Bases& Bs, const BlockRef& cur, const BlockRef& nxt, char* lds, Seam& S) {
;     ...
;     SLOAD_H(Bs.P + nxt.k, Bs.P + nxt.v, Bs.KX + (size_t)nxt.kx * 8, 0, 0); SBAR();
.LBB0_1486:
	s_cmpk_lt_i32 s86, 0x200
	s_cselect_b64 s[70:71], -1, 0
	s_and_b64 s[8:9], s[70:71], exec
	s_cselect_b32 s8, s86, s97
	s_lshl_b32 s9, s8, 8
	s_and_b32 s11, s8, 31
	s_and_b32 s10, s9, 0x1000
	s_lshl_b32 s12, s11, 7
	s_mul_i32 s13, s10, 0x3840
	s_and_b32 s9, s12, 0x780
	s_or_b32 s12, s12, s13
	s_lshl_b32 s14, s12, 1
	s_or_b32 s12, s13, s9
	s_lshl_b32 s12, s12, 1
	v_readlane_b32 s16, v252, 38
	v_readlane_b32 s17, v252, 39
	s_add_u32 s12, s16, s12
	s_addc_u32 s13, s17, 0
	s_add_u32 s12, s12, 0x2000
	s_addc_u32 s13, s13, 0
	s_mul_i32 s100, s99, 0x7080
	s_add_u32 s12, s12, s100
	s_addc_u32 s13, s13, 0
	s_bitset1_b32 s14, 12
	s_add_u32 s14, s16, s14
	s_addc_u32 s15, s17, 0
	s_add_u32 s14, s14, s100
	s_addc_u32 s15, s15, 0
	global_load_dwordx4 v[114:117], v174, s[12:13]
	global_load_dwordx4 v[122:125], v174, s[14:15]
	global_load_dwordx4 v[118:121], v209, s[12:13]
	global_load_dwordx4 v[126:129], v209, s[14:15]
	s_cmp_gt_u32 s2, 63
	s_cbranch_scc1 .LBB0_1488
	s_lshl_b32 s74, s11, 16
	s_lshl_b32 s101, s99, 4
	s_add_i32 s74, s74, s101
	s_cmp_lg_u32 0, -1
	s_mov_b64 s[12:13], src_shared_base
	s_cselect_b32 s11, 0, 0
	s_cselect_b32 s2, s13, 0
	s_add_u32 s12, s11, 0x10800
	s_addc_u32 s13, s2, 0
	s_cmp_lg_u64 s[12:13], 0
	v_lshl_add_u64 v[4:5], v[180:181], 0, s[74:75]
	s_cselect_b32 m0, s12, -1
	s_nop 0
	global_load_lds_dwordx4 v[4:5], off

; __global__ void __launch_bounds__(NWAVES * 64, 2) hyb_fwd(Args args) {
;     extern __shared__ __attribute__((aligned(16))) unsigned char lds[];
	.amdhsa_kernel _Z7hyb_fwd4Args
		.amdhsa_group_segment_fixed_size 0
		.amdhsa_private_segment_fixed_size 0
		.amdhsa_kernarg_size 424
		.amdhsa_user_sgpr_count 2
		.amdhsa_user_sgpr_dispatch_ptr 0
		.amdhsa_user_sgpr_queue_ptr 0
		.amdhsa_user_sgpr_kernarg_segment_ptr 1
		.amdhsa_user_sgpr_dispatch_id 0
		.amdhsa_user_sgpr_kernarg_preload_length 0
		.amdhsa_user_sgpr_kernarg_preload_offset 0
		.amdhsa_user_sgpr_private_segment_size 0
		.amdhsa_uses_dynamic_stack 0
		.amdhsa_enable_private_segment 0
		.amdhsa_system_sgpr_workgroup_id_x 1
		.amdhsa_system_sgpr_workgroup_id_y 0
		.amdhsa_system_sgpr_workgroup_id_z 0
		.amdhsa_system_sgpr_workgroup_info 0
		.amdhsa_system_vgpr_workitem_id 0
		.amdhsa_next_free_vgpr 256
		.amdhsa_next_free_sgpr 102
		.amdhsa_accum_offset 256
		.amdhsa_reserve_vcc 1
		.amdhsa_float_round_mode_32 0
		.amdhsa_float_round_mode_16_64 0
		.amdhsa_float_denorm_mode_32 3
		.amdhsa_float_denorm_mode_16_64 3
		.amdhsa_dx10_clamp 1
		.amdhsa_ieee_mode 1
		.amdhsa_fp16_overflow 0
		.amdhsa_tg_split 0
		.amdhsa_exception_fp_ieee_invalid_op 0
		.amdhsa_exception_fp_denorm_src 0
		.amdhsa_exception_fp_ieee_div_zero 0
		.amdhsa_exception_fp_ieee_overflow 0
		.amdhsa_exception_fp_ieee_underflow 0
		.amdhsa_exception_fp_ieee_inexact 0
		.amdhsa_exception_int_div_zero 0
	.end_amdhsa_kernel

; __global__ void __launch_bounds__(NWAVES * 64, 2) hyb_fwd(Args args) {
;     extern __shared__ __attribute__((aligned(16))) unsigned char lds[];
amdhsa.kernels:
  - .agpr_count:     0
    .args:
      - .offset:         0
        .size:           168
        .value_kind:     by_value
      - .offset:         168
        .size:           4
        .value_kind:     hidden_block_count_x
      - .offset:         172
        .size:           4
        .value_kind:     hidden_block_count_y
      - .offset:         176
        .size:           4
        .value_kind:     hidden_block_count_z
      - .offset:         180
        .size:           2
        .value_kind:     hidden_group_size_x
      - .offset:         182
        .size:           2
        .value_kind:     hidden_group_size_y
      - .offset:         184
        .size:           2
        .value_kind:     hidden_group_size_z
      - .offset:         186
        .size:           2
        .value_kind:     hidden_remainder_x
      - .offset:         188
        .size:           2
        .value_kind:     hidden_remainder_y
      - .offset:         190
        .size:           2
        .value_kind:     hidden_remainder_z
      - .offset:         208
        .size:           8
        .value_kind:     hidden_global_offset_x
      - .offset:         216
        .size:           8
        .value_kind:     hidden_global_offset_y
      - .offset:         224
        .size:           8
        .value_kind:     hidden_global_offset_z
      - .offset:         232
        .size:           2
        .value_kind:     hidden_grid_dims
      - .offset:         288
        .size:           4
        .value_kind:     hidden_dynamic_lds_size
    .group_segment_fixed_size: 0
    .kernarg_segment_align: 8
    .kernarg_segment_size: 424
    .language:       OpenCL C
    .language_version:
      - 2
      - 0
    .max_flat_workgroup_size: 512
    .name:           _Z7hyb_fwd4Args
    .private_segment_fixed_size: 0
    .sgpr_count:     108
    .sgpr_spill_count: 174
    .symbol:         _Z7hyb_fwd4Args.kd
    .uniform_work_group_size: 1
    .uses_dynamic_stack: false
    .vgpr_count:     256
    .vgpr_spill_count: 0
    .wavefront_size: 64
